# mLSTM chunk loop: the four sum_x16/sum_x32 row reductions done with v_permlane16_swap/v_permlane32_swap (VALU) instead of ds_bpermute + lgkmcnt(0) round trips
# speedup vs baseline: 1.0062x; 1.0062x over previous
; __device__ __forceinline__ float sum_x16(float v) { return v + __shfl_xor(v, 16); }
; __device__ __forceinline__ float sum_x32(float v) { return v + __shfl_xor(v, 32); }
; __device__ __forceinline__ void mlstm_unit(const Params& P, LAS unsigned char* lds, int unit) {
;     ...
;                 rsum = sum_x32(sum_x16(rsum));
;                 if (fq == 0) rsS[t * 4 + nt] = rsum;
.LBB0_493:
	s_or_b64 exec, exec, s[18:19]
	s_waitcnt lgkmcnt(0)
	v_and_b32_e32 v141, 64, v178
	v_xor_b32_e32 v140, 16, v178
	v_add_u32_e32 v141, 64, v141
	v_cmp_lt_i32_e32 vcc, v140, v141
	v_xor_b32_e32 v143, 32, v178
	s_nop 0
	v_cndmask_b32_e32 v140, v178, v140, vcc
	v_lshlrev_b32_e32 v140, 2, v140
	v_cmp_lt_i32_e32 vcc, v143, v141
	s_nop 1
	v_cndmask_b32_e32 v141, v178, v143, vcc
	v_lshlrev_b32_e32 v141, 2, v141
	v_mov_b32_e32 v142, v224
	v_mov_b32_e32 v143, v224
	s_nop 1
	v_permlane16_swap_b32_e32 v142, v143
	v_add_f32_e32 v142, v142, v143
	v_mov_b32_e32 v143, v142
	s_nop 1
	v_permlane32_swap_b32_e32 v142, v143
	s_and_saveexec_b64 s[18:19], s[40:41]
	s_cbranch_execz .LBB0_495
	v_add_f32_e32 v142, v142, v143
	ds_write_b32 v196, v142

; __device__ __forceinline__ float sum_x16(float v) { return v + __shfl_xor(v, 16); }
; __device__ __forceinline__ float sum_x32(float v) { return v + __shfl_xor(v, 32); }
; __device__ __forceinline__ void mlstm_unit(const Params& P, LAS unsigned char* lds, int unit) {
;     ...
;                 rsum = sum_x32(sum_x16(rsum));
;                 if (fq == 0) rsS[t * 4 + nt] = rsum;
.LBB0_497:
	s_or_b64 exec, exec, s[18:19]
	s_waitcnt lgkmcnt(0)
	v_mov_b32_e32 v173, v222
	v_mov_b32_e32 v136, v222
	s_nop 1
	v_permlane16_swap_b32_e32 v173, v136
	v_add_f32_e32 v173, v173, v136
	v_mov_b32_e32 v136, v173
	s_nop 1
	v_permlane32_swap_b32_e32 v173, v136
	s_and_saveexec_b64 s[18:19], s[40:41]
	s_cbranch_execz .LBB0_499
	v_add_f32_e32 v173, v173, v136
	ds_write_b32 v196, v173 offset:4
